# acquire hoist extended: also chip-wide seam 0, and batch seams 8,9 when the batch shares one XCD (runtime census flag), else invalidate stays after the wait
# speedup vs baseline: 1.0096x; 1.0046x over previous
.LBB0_1615:
	s_or_b64 exec, exec, s[6:7]
	v_mov_b32_e32 v1, 0
	global_load_dword v4, v1, s[2:3] sc1
	s_cmp_lg_u32 s98, 0
	s_cbranch_scc0 .Lei_a5
	buffer_inv sc1
.Lei_a5:
	s_waitcnt vmcnt(1)
	v_readfirstlane_b32 s4, v3
	s_nop 1
	v_add_u32_e32 v2, s4, v2
	v_and_b32_e32 v2, -8, v2
	v_add_u32_e32 v2, 8, v2
	s_waitcnt vmcnt(0)
	v_cmp_lt_u32_e32 vcc, v4, v2
	s_and_saveexec_b64 s[4:5], vcc
	s_cbranch_execz .LBB0_1627
	s_add_u32 s6, s82, 0x4200
	s_addc_u32 s7, s83, 0
	s_mov_b32 s18, 1
	s_mov_b64 s[8:9], 0
	s_branch .LBB0_1618

.LBB0_1627:
	s_or_b64 exec, exec, s[4:5]
	s_waitcnt vmcnt(0)
	s_cmp_lg_u32 s98, 0
	s_cbranch_scc1 .Lei_b5
	buffer_inv sc1
.Lei_b5:
	s_waitcnt vmcnt(0)
.LBB0_1628:
	s_or_b64 exec, exec, s[0:1]
	s_barrier

.Lei_a6:
	s_waitcnt vmcnt(1)
	v_readfirstlane_b32 s4, v3
	s_nop 1
	v_add_u32_e32 v2, s4, v2
	v_and_b32_e32 v2, 0xffffffe0, v2
	v_add_u32_e32 v2, 32, v2
	s_waitcnt vmcnt(0)
	v_cmp_lt_u32_e32 vcc, v4, v2
	s_and_saveexec_b64 s[4:5], vcc
	s_cbranch_execz .LBB0_1781
	s_add_u32 s6, s82, 0x4200
	s_addc_u32 s7, s83, 0
	s_mov_b32 s18, 1
	s_mov_b64 s[8:9], 0
	s_branch .LBB0_1772

.Lei_b6:
	s_waitcnt vmcnt(0)
.LBB0_1782:
	s_or_b64 exec, exec, s[0:1]
	s_barrier
